# v63 + MLA steady step: the 16 V fragment reads issued as 8 pairs, one pair behind each QK MFMA 5..12, instead of two bursts of 8
# speedup vs baseline: 1.0052x; 1.0052x over previous
.LBB0_1478:
	s_waitcnt lgkmcnt(9)
	v_mfma_f32_32x32x16_bf16 v[66:81], v[162:165], v[106:109], v[66:81]
	s_waitcnt lgkmcnt(8)
	v_mfma_f32_32x32x16_bf16 v[82:97], v[150:153], v[106:109], v[82:97]
	s_add_u32 s26, s0, s24
	s_addc_u32 s27, s53, s25
	s_lshl_b32 s51, s57, 13
	s_add_i32 s98, s51, s43
	s_mov_b32 s99, m0
	s_mov_b32 m0, s98
	s_nop 0
	global_load_lds_dwordx4 v181, s[26:27]
	s_mov_b32 m0, s99
	s_waitcnt lgkmcnt(7)
	v_mfma_f32_32x32x16_bf16 v[66:81], v[146:149], v[102:105], v[66:81]
	ds_read_b64_tr_b16 v[150:151], v158 offset:24576
	ds_read_b64_tr_b16 v[152:153], v158 offset:25088
	s_waitcnt lgkmcnt(8)
	v_mfma_f32_32x32x16_bf16 v[82:97], v[142:145], v[102:105], v[82:97]
	ds_read_b64_tr_b16 v[146:147], v158 offset:25600
	ds_read_b64_tr_b16 v[148:149], v158 offset:26112
	s_waitcnt lgkmcnt(9)
	v_mfma_f32_32x32x16_bf16 v[66:81], v[138:141], v[114:117], v[66:81]
	ds_read_b64_tr_b16 v[142:143], v158 offset:26624
	ds_read_b64_tr_b16 v[144:145], v158 offset:27136
	s_waitcnt lgkmcnt(10)
	v_mfma_f32_32x32x16_bf16 v[82:97], v[134:137], v[114:117], v[82:97]
	ds_read_b64_tr_b16 v[138:139], v158 offset:27648
	ds_read_b64_tr_b16 v[140:141], v158 offset:28160
	s_waitcnt lgkmcnt(11)
	v_mfma_f32_32x32x16_bf16 v[66:81], v[130:133], v[110:113], v[66:81]
	ds_read_b64_tr_b16 v[134:135], v158 offset:28672
	ds_read_b64_tr_b16 v[136:137], v158 offset:29184
	s_waitcnt lgkmcnt(12)
	v_mfma_f32_32x32x16_bf16 v[82:97], v[126:129], v[110:113], v[82:97]
	ds_read_b64_tr_b16 v[130:131], v158 offset:29696
	ds_read_b64_tr_b16 v[132:133], v158 offset:30208
	s_waitcnt lgkmcnt(13)
	v_mfma_f32_32x32x16_bf16 v[66:81], v[122:125], v[118:121], v[66:81]
	ds_read_b64_tr_b16 v[126:127], v158 offset:30720
	ds_read_b64_tr_b16 v[128:129], v158 offset:31232
	s_waitcnt lgkmcnt(14)
	v_mfma_f32_32x32x16_bf16 v[82:97], v[154:157], v[118:121], v[82:97]
	ds_read_b64_tr_b16 v[122:123], v158 offset:31744
	ds_read_b64_tr_b16 v[124:125], v158 offset:32256
	s_cmp_lg_u32 s101, 0
	s_cbranch_scc0 .Lmla2_slow
	s_nop 4
.LBB0_1482:
	v_exp_f32_e32 v66, v66
	v_exp_f32_e32 v67, v67
	v_exp_f32_e32 v68, v68
	v_exp_f32_e32 v69, v69
	v_exp_f32_e32 v70, v70
	v_exp_f32_e32 v71, v71
	v_exp_f32_e32 v72, v72
	v_exp_f32_e32 v73, v73
	v_pk_add_f32 v[154:155], v[66:67], v[68:69]
	v_pk_add_f32 v[156:157], v[70:71], v[72:73]
	v_pk_add_f32 v[158:159], v[154:155], v[156:157]
	v_cvt_pk_bf16_f32 v66, v66, v67
	v_cvt_pk_bf16_f32 v67, v68, v69
	v_cvt_pk_bf16_f32 v68, v70, v71
	v_cvt_pk_bf16_f32 v69, v72, v73
	v_exp_f32_e32 v74, v74
	v_exp_f32_e32 v75, v75
	s_waitcnt lgkmcnt(14)
	v_mfma_f32_32x32x16_bf16 v[18:33], v[66:69], v[150:153], v[18:33]
	v_exp_f32_e32 v76, v76
	v_exp_f32_e32 v77, v77
	v_exp_f32_e32 v78, v78
	s_waitcnt lgkmcnt(6)
	v_mfma_f32_32x32x16_bf16 v[34:49], v[66:69], v[134:137], v[34:49]
	v_exp_f32_e32 v79, v79
	v_exp_f32_e32 v80, v80
	v_exp_f32_e32 v81, v81
	v_pk_add_f32 v[154:155], v[74:75], v[76:77]
	v_pk_add_f32 v[156:157], v[78:79], v[80:81]
	v_pk_add_f32 v[160:161], v[154:155], v[156:157]
	v_cvt_pk_bf16_f32 v70, v74, v75
	v_cvt_pk_bf16_f32 v71, v76, v77
	v_cvt_pk_bf16_f32 v72, v78, v79
	v_cvt_pk_bf16_f32 v73, v80, v81
	v_exp_f32_e32 v82, v82
	v_exp_f32_e32 v83, v83
	v_mfma_f32_32x32x16_bf16 v[18:33], v[70:73], v[146:149], v[18:33]
	v_exp_f32_e32 v84, v84
	v_exp_f32_e32 v85, v85
	v_exp_f32_e32 v86, v86
	s_waitcnt lgkmcnt(4)
	v_mfma_f32_32x32x16_bf16 v[34:49], v[70:73], v[130:133], v[34:49]
	v_exp_f32_e32 v87, v87
	v_exp_f32_e32 v88, v88
	v_exp_f32_e32 v89, v89
	v_pk_add_f32 v[154:155], v[82:83], v[84:85]
	v_pk_add_f32 v[156:157], v[86:87], v[88:89]
	v_pk_add_f32 v[162:163], v[154:155], v[156:157]
	v_cvt_pk_bf16_f32 v74, v82, v83
	v_cvt_pk_bf16_f32 v75, v84, v85
	v_cvt_pk_bf16_f32 v76, v86, v87
	v_cvt_pk_bf16_f32 v77, v88, v89
	v_exp_f32_e32 v90, v90
	v_exp_f32_e32 v91, v91
	v_mfma_f32_32x32x16_bf16 v[18:33], v[74:77], v[142:145], v[18:33]
	v_exp_f32_e32 v92, v92
	v_exp_f32_e32 v93, v93
	v_exp_f32_e32 v94, v94
	s_waitcnt lgkmcnt(2)
	v_mfma_f32_32x32x16_bf16 v[34:49], v[74:77], v[126:129], v[34:49]
	v_exp_f32_e32 v95, v95
	v_exp_f32_e32 v96, v96
	v_exp_f32_e32 v97, v97
	v_pk_add_f32 v[154:155], v[90:91], v[92:93]
	v_pk_add_f32 v[156:157], v[94:95], v[96:97]
	v_pk_add_f32 v[164:165], v[154:155], v[156:157]
	v_cvt_pk_bf16_f32 v78, v90, v91
	v_cvt_pk_bf16_f32 v79, v92, v93
	v_cvt_pk_bf16_f32 v80, v94, v95
	v_cvt_pk_bf16_f32 v81, v96, v97
	v_pk_add_f32 v[158:159], v[158:159], v[160:161]
	s_add_u32 s24, s24, 0x10000
	s_addc_u32 s25, s25, 0
	v_mfma_f32_32x32x16_bf16 v[18:33], v[78:81], v[138:141], v[18:33]
	v_pk_add_f32 v[162:163], v[162:163], v[164:165]
	s_add_u32 s22, s22, 0x1000
	s_addc_u32 s23, s23, 0
	s_waitcnt lgkmcnt(0)
	v_mfma_f32_32x32x16_bf16 v[34:49], v[78:81], v[122:125], v[34:49]
	v_pk_add_f32 v[158:159], v[158:159], v[162:163]
	v_add_f32_e32 v158, v158, v159
	v_add_u32_e32 v66, s56, v182
	v_add_f32_e32 v173, v173, v158
	v_add_u32_e32 v67, v66, v184
	v_add_u32_e32 v66, v66, v189
	s_cmp_eq_u32 s24, 0x200000
	s_waitcnt vmcnt(0) lgkmcnt(0)
	s_barrier
	ds_read_b128 v[82:85], v67
	s_cbranch_scc1 .LBB0_1484
	s_mov_b32 s49, s57
	s_mul_i32 s52, s49, 0x3000
	s_branch .Lmla2_reads2
